# decode loop: counted vmcnt(10) waits (true 2-tile prefetch), page-table entry via s_load_dword instead of global_load+vmcnt(0) drain
# speedup vs baseline: 1.0080x; 1.0080x over previous
.LBB0_874:
	s_lshl_b32 s0, s84, 6
	s_ashr_i32 s1, s0, 31
	v_readlane_b32 s44, v255, 26
	s_bfe_u32 s25, s83, 0x10001
	s_and_b32 s85, s14, 3
	s_lshl_b64 s[0:1], s[0:1], 2
	v_readlane_b32 s46, v255, 28
	v_readlane_b32 s47, v255, 29
	s_add_u32 s4, s46, s0
	s_mul_i32 s62, s25, 0x41
	s_addc_u32 s5, s47, s1
	s_lshl_b32 s2, s62, 1
	s_and_b32 s2, s2, 0xfc
	s_add_i32 s3, s62, 1
	v_mov_b32_e32 v8, s2
	s_lshl_b32 s2, s3, 1
	s_and_b32 s2, s2, 0x1fc
	v_mov_b32_e32 v9, s2
	global_load_dword v8, v8, s[4:5]
	s_lshl_b32 s54, s25, 6
	global_load_dword v9, v9, s[4:5]
	s_ashr_i32 s15, s14, 2
	s_add_i32 s86, s54, 0x41
	v_readlane_b32 s45, v255, 27
	v_lshrrev_b32_e32 v205, 4, v159
	v_lshlrev_b32_e32 v206, 4, v159
	v_lshlrev_b32_e32 v158, 3, v159
	s_cmp_ge_u32 s62, s86
	s_waitcnt vmcnt(1)
	v_readfirstlane_b32 s2, v8
	s_waitcnt vmcnt(0)
	v_readfirstlane_b32 s4, v9
	s_cbranch_scc1 .LBB0_904
	v_ashrrev_i32_e32 v8, 4, v0
	s_movk_i32 s5, 0x2a0
	v_mul_lo_u32 v10, v8, s5
	v_mad_u64_u32 v[192:193], s[10:11], v134, s5, v[158:159]
	s_ashr_i32 s5, s4, 31
	s_lshl_b32 s3, s3, 6
	s_lshl_b64 s[4:5], s[4:5], 7
	s_and_b32 s3, s3, 64
	s_or_b32 s4, s4, s3
	s_lshl_b64 s[10:11], s[4:5], 8
	s_add_u32 s10, s44, s10
	s_addc_u32 s11, s45, s11
	s_lshl_b64 s[4:5], s[4:5], 10
	s_add_u32 s4, s42, s4
	v_lshlrev_b32_e32 v9, 4, v204
	s_addc_u32 s5, s43, s5
	s_ashr_i32 s3, s2, 31
	v_lshl_or_b32 v160, v134, 10, v206
	v_lshl_or_b32 v176, v8, 8, v9
	s_lshl_b64 s[2:3], s[2:3], 7
	v_add_u32_e32 v174, 0xe000, v160
	v_add_u32_e32 v178, 0x2000, v176
	s_or_b32 s2, s2, s54
	v_add_u32_e32 v162, 0x2000, v160
	v_add_u32_e32 v164, 0x4000, v160
	v_add_u32_e32 v166, 0x6000, v160
	v_add_u32_e32 v168, 0x8000, v160
	v_add_u32_e32 v170, 0xa000, v160
	v_add_u32_e32 v172, 0xc000, v160
	global_load_dwordx4 v[104:107], v178, s[10:11] nt
	global_load_dwordx4 v[76:79], v176, s[10:11] nt
	global_load_dwordx4 v[116:119], v174, s[4:5] nt
	global_load_dwordx4 v[112:115], v172, s[4:5] nt
	global_load_dwordx4 v[108:111], v170, s[4:5] nt
	global_load_dwordx4 v[100:103], v168, s[4:5] nt
	global_load_dwordx4 v[96:99], v166, s[4:5] nt
	global_load_dwordx4 v[92:95], v164, s[4:5] nt
	global_load_dwordx4 v[88:91], v162, s[4:5] nt
	global_load_dwordx4 v[80:83], v160, s[4:5] nt
	s_lshl_b64 s[4:5], s[2:3], 8
	s_add_u32 s4, s44, s4
	s_addc_u32 s5, s45, s5
	s_lshl_b64 s[2:3], s[2:3], 10
	s_add_u32 s2, s42, s2
	s_addc_u32 s3, s43, s3
	global_load_dwordx4 v[124:127], v178, s[4:5] nt
	global_load_dwordx4 v[84:87], v176, s[4:5] nt
	global_load_dwordx4 v[128:131], v174, s[2:3] nt
	global_load_dwordx4 v[132:135], v172, s[2:3] nt
	global_load_dwordx4 v[136:139], v170, s[2:3] nt
	global_load_dwordx4 v[140:143], v168, s[2:3] nt
	global_load_dwordx4 v[144:147], v166, s[2:3] nt
	global_load_dwordx4 v[148:151], v164, s[2:3] nt
	global_load_dwordx4 v[152:155], v162, s[2:3] nt
	global_load_dwordx4 v[120:123], v160, s[2:3] nt
	v_mov_b32_e32 v8, v5
	v_mov_b32_e32 v9, v6
	v_mov_b32_e32 v5, v7
	v_pk_add_f32 v[4:5], v[8:9], v[4:5]
	s_add_u32 s2, s30, s6
	v_add_f32_e32 v4, v4, v5
	v_fmamk_f32 v4, v4, 0x3b800000, v222
	v_rsq_f32_e32 v194, v4
	v_lshlrev_b32_e32 v4, 2, v0
	v_ashrrev_i32_e32 v5, 31, v4
	s_addc_u32 s3, s31, s7
	v_lshlrev_b64 v[4:5], 2, v[4:5]
	v_lshl_add_u64 v[196:197], s[2:3], 0, v[4:5]
	v_readlane_b32 s2, v255, 12
	v_readlane_b32 s3, v255, 13
	s_mul_i32 s34, s25, 0x82
	v_cmp_gt_i32_e64 s[4:5], 64, v0
	v_lshl_add_u64 v[200:201], s[2:3], 0, v[4:5]
	s_lshl_b64 s[2:3], s[8:9], 8
	s_add_u32 s2, s57, s2
	s_addc_u32 s3, s93, s3
	v_lshl_add_u64 v[202:203], s[2:3], 0, v[4:5]
	s_lshl_b32 s2, s85, 4
	s_bitcmp1_b32 s83, 1
	v_cmp_gt_i32_e64 s[6:7], 16, v0
	v_or_b32_e32 v0, s2, v204
	v_lshl_or_b32 v5, v205, 2, s2
	s_cselect_b32 s2, 0xa800, 0
	s_cselect_b32 s3, 0, 0xa800
	s_add_i32 s26, s34, 6
	s_add_i32 s2, s2, 0
	s_add_i32 s3, s3, 0
	s_and_b32 s26, s26, 0x1fc
	s_add_u32 s26, s26, s0
	s_addc_u32 s27, 0, s1
	s_add_u32 s26, s46, s26
	s_addc_u32 s27, s47, s27
	s_mul_i32 s35, s25, 0x1040
	s_add_i32 s34, s34, 4
	s_add_i32 s50, s35, 0xc0
	s_and_b32 s34, s34, 0x1fc
	v_lshrrev_b32_e32 v6, 2, v204
	v_lshlrev_b32_e32 v3, 3, v3
	s_add_u32 s0, s34, s0
	v_or_b32_e32 v6, v5, v6
	v_and_b32_e32 v3, 24, v3
	s_addc_u32 s1, 0, s1
	v_mul_u32_u24_e32 v0, 0x2a0, v0
	v_or_b32_e32 v4, s85, v205
	v_mul_u32_u24_e32 v6, 0x2a0, v6
	v_lshl_or_b32 v3, s15, 8, v3
	s_add_u32 s34, s46, s0
	v_mov_b32_e32 v157, 0
	v_mov_b32_e32 v161, v2
	v_mov_b32_e32 v163, v2
	v_mov_b32_e32 v165, v2
	v_mov_b32_e32 v167, v2
	v_mov_b32_e32 v169, v2
	v_mov_b32_e32 v171, v2
	v_mov_b32_e32 v173, v2
	v_mov_b32_e32 v175, v2
	v_mov_b32_e32 v177, v2
	v_mov_b32_e32 v179, v2
	v_mov_b32_e32 v198, v194
	v_mov_b32_e32 v199, v194
	v_cmp_eq_u32_e64 s[8:9], 0, v4
	v_cmp_eq_u32_e64 s[10:11], 0, v5
	v_lshl_add_u32 v193, v204, 3, v10
	v_add3_u32 v207, s2, v0, v1
	v_add3_u32 v208, s2, v6, v3
	v_add3_u32 v209, s3, v0, v1
	v_add3_u32 v210, s3, v6, v3
	s_addc_u32 s35, s47, s1
	v_mov_b32_e32 v156, 0xf149f2ca
	v_mov_b32_e32 v4, 0
	v_mov_b32_e32 v5, v157
	v_mov_b32_e32 v6, v157
	v_mov_b32_e32 v7, v157
	v_mov_b32_e32 v8, v157
	v_mov_b32_e32 v9, v157
	v_mov_b32_e32 v10, v157
	v_mov_b32_e32 v11, v157
	v_mov_b32_e32 v52, v157
	v_mov_b32_e32 v53, v157
	v_mov_b32_e32 v54, v157
	v_mov_b32_e32 v55, v157
	v_mov_b32_e32 v56, v157
	v_mov_b32_e32 v57, v157
	v_mov_b32_e32 v58, v157
	v_mov_b32_e32 v59, v157
	v_mov_b32_e32 v60, v157
	v_mov_b32_e32 v61, v157
	v_mov_b32_e32 v62, v157
	v_mov_b32_e32 v63, v157
	v_mov_b32_e32 v64, v157
	v_mov_b32_e32 v65, v157
	v_mov_b32_e32 v66, v157
	v_mov_b32_e32 v67, v157
	v_mov_b32_e32 v68, v157
	v_mov_b32_e32 v69, v157
	v_mov_b32_e32 v70, v157
	v_mov_b32_e32 v71, v157
	v_mov_b32_e32 v72, v157
	v_mov_b32_e32 v73, v157
	v_mov_b32_e32 v74, v157
	v_mov_b32_e32 v75, v157
	s_waitcnt vmcnt(0)
.LBB0_876:
	s_add_i32 s100, s62, 2
	s_cmp_lt_u32 s100, s86
	s_cbranch_scc1 .Ldec_topA_cnt
	s_waitcnt vmcnt(0)
	s_branch .Ldec_topA_go
.Ldec_topA_cnt:
	s_waitcnt vmcnt(10)
.Ldec_topA_go:
	v_cvt_pk_bf16_f32 v0, v120, v121
	v_cvt_pk_bf16_f32 v1, v122, v123
	v_add_u32_e32 v3, s2, v192
	ds_write_b64 v3, v[0:1]
	v_cvt_pk_bf16_f32 v0, v152, v153
	v_cvt_pk_bf16_f32 v1, v154, v155
	ds_write_b64 v3, v[0:1] offset:5376
	v_cvt_pk_bf16_f32 v0, v148, v149
	v_cvt_pk_bf16_f32 v1, v150, v151
	ds_write_b64 v3, v[0:1] offset:10752
	v_cvt_pk_bf16_f32 v0, v144, v145
	v_cvt_pk_bf16_f32 v1, v146, v147
	ds_write_b64 v3, v[0:1] offset:16128
	v_cvt_pk_bf16_f32 v0, v140, v141
	v_cvt_pk_bf16_f32 v1, v142, v143
	ds_write_b64 v3, v[0:1] offset:21504
	v_cvt_pk_bf16_f32 v0, v136, v137
	v_cvt_pk_bf16_f32 v1, v138, v139
	ds_write_b64 v3, v[0:1] offset:26880
	v_cvt_pk_bf16_f32 v0, v132, v133
	v_cvt_pk_bf16_f32 v1, v134, v135
	ds_write_b64 v3, v[0:1] offset:32256
	v_cvt_pk_bf16_f32 v0, v128, v129
	v_cvt_pk_bf16_f32 v1, v130, v131
	ds_write_b64 v3, v[0:1] offset:37632
	v_cvt_pk_bf16_f32 v0, v84, v85
	v_cvt_pk_bf16_f32 v1, v86, v87
	v_add_u32_e32 v3, s2, v193
	v_cvt_pk_bf16_f32 v180, v124, v125
	v_cvt_pk_bf16_f32 v181, v126, v127
	ds_write2st64_b64 v3, v[0:1], v[180:181] offset0:1 offset1:43
	s_add_i32 s51, s62, 2
	s_waitcnt lgkmcnt(0)
	s_barrier
	s_cmp_ge_u32 s51, s86
	s_cselect_b64 s[44:45], -1, 0
	s_and_b64 vcc, exec, s[44:45]
	s_cbranch_vccnz .LBB0_886
	s_cmpk_lt_u32 s62, 0x7e
	s_mov_b64 s[0:1], -1
	s_cbranch_scc1 .LBB0_883
	v_mov_b32_e32 v86, v2
	v_mov_b32_e32 v87, v2
	v_mov_b32_e32 v84, 0
	v_mov_b32_e32 v85, v2
	v_mov_b64_e32 v[122:123], v[86:87]
	v_mov_b64_e32 v[120:121], v[84:85]
	s_and_saveexec_b64 s[0:1], s[4:5]
	s_cbranch_execz .LBB0_880
	global_load_dwordx4 v[120:123], v[196:197], off
	v_mov_b32_e32 v195, v194
	s_waitcnt vmcnt(0)
	v_pk_mul_f32 v[0:1], v[194:195], v[122:123]
	v_pk_mul_f32 v[124:125], v[198:199], v[120:121]
	global_load_dwordx4 v[120:123], v[200:201], off
	s_waitcnt vmcnt(0)
	v_pk_mul_f32 v[122:123], v[0:1], v[122:123]
	v_pk_mul_f32 v[120:121], v[124:125], v[120:121]

.LBB0_883:
	s_and_b64 vcc, exec, s[0:1]
	s_cbranch_vccz .LBB0_885
	s_load_dword s0, s[34:35], 0x0
	s_waitcnt lgkmcnt(0)
	s_ashr_i32 s1, s0, 31
	s_lshl_b64 s[0:1], s[0:1], 7
	s_or_b64 s[0:1], s[0:1], s[54:55]
	s_lshl_b64 s[64:65], s[0:1], 10
	s_add_u32 s64, s42, s64
	s_addc_u32 s65, s43, s65
	v_lshl_add_u64 v[0:1], s[64:65], 0, v[160:161]
	v_lshl_add_u64 v[128:129], s[64:65], 0, v[170:171]
	v_lshl_add_u64 v[130:131], s[64:65], 0, v[172:173]
	v_lshl_add_u64 v[84:85], s[64:65], 0, v[162:163]
	v_lshl_add_u64 v[86:87], s[64:65], 0, v[164:165]
	v_lshl_add_u64 v[124:125], s[64:65], 0, v[166:167]
	v_lshl_add_u64 v[126:127], s[64:65], 0, v[168:169]
	v_lshl_add_u64 v[180:181], s[64:65], 0, v[174:175]
	global_load_dwordx4 v[120:123], v[0:1], off nt
	global_load_dwordx4 v[152:155], v[84:85], off nt
	global_load_dwordx4 v[148:151], v[86:87], off nt
	global_load_dwordx4 v[144:147], v[124:125], off nt
	global_load_dwordx4 v[140:143], v[126:127], off nt
	global_load_dwordx4 v[136:139], v[128:129], off nt
	global_load_dwordx4 v[132:135], v[130:131], off nt
	s_nop 0
	global_load_dwordx4 v[128:131], v[180:181], off nt
	s_lshl_b64 s[0:1], s[0:1], 8
	v_readlane_b32 s64, v255, 26
	v_readlane_b32 s65, v255, 27
	s_add_u32 s0, s64, s0
	s_addc_u32 s1, s65, s1
	v_lshl_add_u64 v[0:1], s[0:1], 0, v[176:177]
	v_lshl_add_u64 v[124:125], s[0:1], 0, v[178:179]
	global_load_dwordx4 v[84:87], v[0:1], off nt
	s_nop 0
	global_load_dwordx4 v[124:127], v[124:125], off nt
	v_readlane_b32 s66, v255, 28
	v_readlane_b32 s67, v255, 29
	s_branch .LBB0_886

.LBB0_888:
	v_sub_f32_e32 v180, v195, v156
	v_mul_f32_e32 v180, 0x3dd53b94, v180
	v_sub_f32_e32 v3, v3, v156
	v_exp_f32_e32 v180, v180
	v_mul_f32_e32 v3, 0x3dd53b94, v3
	v_sub_f32_e32 v1, v1, v156
	v_exp_f32_e32 v3, v3
	v_mul_f32_e32 v1, 0x3dd53b94, v1
	v_sub_f32_e32 v0, v0, v156
	v_exp_f32_e32 v1, v1
	v_mul_f32_e32 v0, 0x3dd53b94, v0
	v_exp_f32_e32 v182, v0
	v_add_f32_e32 v181, 0, v180
	v_add_f32_e32 v181, v3, v181
	v_add_f32_e32 v181, v1, v181
	v_add_f32_e32 v0, v182, v181
	v_mov_b32_e32 v181, v0
	s_nop 1
	v_permlane16_swap_b32_e32 v0, v181
	v_add_f32_e32 v0, v0, v181
	v_mov_b32_e32 v181, v0
	s_nop 1
	v_permlane32_swap_b32_e32 v0, v181
	v_add_f32_e32 v195, v0, v181
	v_cvt_pk_bf16_f32 v0, v180, v3
	ds_read_b64_tr_b16 v[180:181], v208 offset:0
	ds_read_b64_tr_b16 v[184:185], v208 offset:32
	ds_read_b64_tr_b16 v[188:189], v208 offset:64
	ds_read_b64_tr_b16 v[212:213], v208 offset:0x60
	ds_read_b64_tr_b16 v[216:217], v208 offset:0x80
	ds_read_b64_tr_b16 v[230:231], v208 offset:0xa0
	ds_read_b64_tr_b16 v[234:235], v208 offset:0xc0
	ds_read_b64_tr_b16 v[238:239], v208 offset:0xe0
	v_cvt_pk_bf16_f32 v1, v1, v182
	s_waitcnt lgkmcnt(0)
	v_mov_b32_e32 v3, v2
	v_mov_b32_e32 v182, v180
	v_mov_b32_e32 v183, v181
	v_mov_b32_e32 v186, v184
	v_mov_b32_e32 v187, v185
	v_mov_b32_e32 v190, v188
	v_mov_b32_e32 v191, v189
	v_mov_b32_e32 v214, v212
	v_mov_b32_e32 v215, v213
	v_mov_b32_e32 v218, v216
	v_mov_b32_e32 v219, v217
	v_mov_b32_e32 v232, v230
	v_mov_b32_e32 v233, v231
	v_mov_b32_e32 v236, v234
	v_mov_b32_e32 v237, v235
	v_mov_b32_e32 v240, v238
	v_mov_b32_e32 v241, v239
	v_mfma_f32_16x16x32_bf16 v[4:7], v[180:183], v[0:3], v[4:7]
	s_add_i32 s0, s62, 1
	v_add_f32_e32 v157, v157, v195
	s_cmp_ge_u32 s0, s86
	v_mfma_f32_16x16x32_bf16 v[8:11], v[184:187], v[0:3], v[8:11]
	v_mfma_f32_16x16x32_bf16 v[52:55], v[188:191], v[0:3], v[52:55]
	v_mfma_f32_16x16x32_bf16 v[56:59], v[212:215], v[0:3], v[56:59]
	v_mfma_f32_16x16x32_bf16 v[60:63], v[216:219], v[0:3], v[60:63]
	v_mfma_f32_16x16x32_bf16 v[64:67], v[230:233], v[0:3], v[64:67]
	v_mfma_f32_16x16x32_bf16 v[68:71], v[234:237], v[0:3], v[68:71]
	v_mfma_f32_16x16x32_bf16 v[72:75], v[238:241], v[0:3], v[72:75]
	s_cbranch_scc1 .LBB0_902
	s_add_i32 s100, s62, 3
	s_cmp_lt_u32 s100, s86
	s_cbranch_scc1 .Ldec_topB_cnt
	s_waitcnt vmcnt(0)
	s_branch .Ldec_topB_go

.Ldec_topB_go:
	v_cvt_pk_bf16_f32 v0, v80, v81
	v_cvt_pk_bf16_f32 v1, v82, v83
	v_add_u32_e32 v3, s3, v192
	ds_write_b64 v3, v[0:1]
	v_cvt_pk_bf16_f32 v0, v88, v89
	v_cvt_pk_bf16_f32 v1, v90, v91
	ds_write_b64 v3, v[0:1] offset:5376
	v_cvt_pk_bf16_f32 v0, v92, v93
	v_cvt_pk_bf16_f32 v1, v94, v95
	ds_write_b64 v3, v[0:1] offset:10752
	v_cvt_pk_bf16_f32 v0, v96, v97
	v_cvt_pk_bf16_f32 v1, v98, v99
	ds_write_b64 v3, v[0:1] offset:16128
	v_cvt_pk_bf16_f32 v0, v100, v101
	v_cvt_pk_bf16_f32 v1, v102, v103
	ds_write_b64 v3, v[0:1] offset:21504
	v_cvt_pk_bf16_f32 v0, v108, v109
	v_cvt_pk_bf16_f32 v1, v110, v111
	ds_write_b64 v3, v[0:1] offset:26880
	v_cvt_pk_bf16_f32 v0, v112, v113
	v_cvt_pk_bf16_f32 v1, v114, v115
	ds_write_b64 v3, v[0:1] offset:32256
	v_cvt_pk_bf16_f32 v0, v116, v117
	v_cvt_pk_bf16_f32 v1, v118, v119
	ds_write_b64 v3, v[0:1] offset:37632
	v_cvt_pk_bf16_f32 v0, v76, v77
	v_cvt_pk_bf16_f32 v1, v78, v79
	v_add_u32_e32 v3, s3, v193
	v_cvt_pk_bf16_f32 v180, v104, v105
	v_cvt_pk_bf16_f32 v181, v106, v107
	ds_write2st64_b64 v3, v[0:1], v[180:181] offset0:1 offset1:43
	s_waitcnt lgkmcnt(0)
	s_barrier
	s_add_i32 s0, s62, 3
	s_cmp_ge_u32 s0, s86
	s_cbranch_scc1 .LBB0_899
	s_cmpk_lt_u32 s62, 0x7d
	s_mov_b64 s[0:1], -1
	s_cbranch_scc1 .LBB0_896
	v_mov_b32_e32 v78, v2
	v_mov_b32_e32 v79, v2
	v_mov_b32_e32 v76, 0
	v_mov_b32_e32 v77, v2
	v_mov_b64_e32 v[82:83], v[78:79]
	v_mov_b64_e32 v[80:81], v[76:77]
	s_and_saveexec_b64 s[0:1], s[4:5]
	s_cbranch_execz .LBB0_893
	global_load_dwordx4 v[80:83], v[196:197], off
	v_mov_b32_e32 v195, v194
	s_waitcnt vmcnt(0)
	v_pk_mul_f32 v[0:1], v[194:195], v[82:83]
	v_pk_mul_f32 v[88:89], v[198:199], v[80:81]
	global_load_dwordx4 v[80:83], v[200:201], off
	s_waitcnt vmcnt(0)
	v_pk_mul_f32 v[82:83], v[0:1], v[82:83]
	v_pk_mul_f32 v[80:81], v[88:89], v[80:81]

.LBB0_896:
	s_and_b64 vcc, exec, s[0:1]
	s_cbranch_vccz .LBB0_898
	s_load_dword s0, s[26:27], 0x0
	s_and_b32 s64, s50, 64
	s_waitcnt lgkmcnt(0)
	s_ashr_i32 s1, s0, 31
	s_lshl_b64 s[0:1], s[0:1], 7
	s_or_b32 s0, s0, s64
	s_lshl_b64 s[64:65], s[0:1], 10
	s_add_u32 s64, s42, s64
	s_addc_u32 s65, s43, s65
	v_lshl_add_u64 v[0:1], s[64:65], 0, v[160:161]
	v_lshl_add_u64 v[96:97], s[64:65], 0, v[166:167]
	v_lshl_add_u64 v[100:101], s[64:65], 0, v[168:169]
	v_lshl_add_u64 v[116:117], s[64:65], 0, v[174:175]
	v_lshl_add_u64 v[76:77], s[64:65], 0, v[162:163]
	v_lshl_add_u64 v[78:79], s[64:65], 0, v[164:165]
	v_lshl_add_u64 v[104:105], s[64:65], 0, v[170:171]
	v_lshl_add_u64 v[106:107], s[64:65], 0, v[172:173]
	global_load_dwordx4 v[80:83], v[0:1], off nt
	global_load_dwordx4 v[88:91], v[76:77], off nt
	global_load_dwordx4 v[92:95], v[78:79], off nt
	s_nop 0
	global_load_dwordx4 v[96:99], v[96:97], off nt
	s_nop 0
	global_load_dwordx4 v[100:103], v[100:101], off nt
	s_nop 0
	global_load_dwordx4 v[108:111], v[104:105], off nt
	global_load_dwordx4 v[112:115], v[106:107], off nt
	s_nop 0
	global_load_dwordx4 v[116:119], v[116:117], off nt
	s_lshl_b64 s[0:1], s[0:1], 8
	v_readlane_b32 s64, v255, 26
	v_readlane_b32 s65, v255, 27
	s_add_u32 s0, s64, s0
	s_addc_u32 s1, s65, s1
	v_lshl_add_u64 v[0:1], s[0:1], 0, v[176:177]
	v_lshl_add_u64 v[104:105], s[0:1], 0, v[178:179]
	global_load_dwordx4 v[76:79], v[0:1], off nt
	s_nop 0
	global_load_dwordx4 v[104:107], v[104:105], off nt
	v_readlane_b32 s66, v255, 28
	v_readlane_b32 s67, v255, 29
	s_branch .LBB0_899
